# v37 plus: P1 conversion waves paced (s_sleep 80 per item) so their HBM traffic spreads over the whole adaLN weight-stream chain instead of front-loading it
# speedup vs baseline: 1.0006x; 1.0006x over previous
; __device__ __forceinline__ void phase_ada_conv(const Frame& F) {
;     ...
;         else { const int cw = pair * 7 + (odd ? 3 + (F.wave - 4) : (F.wave - 5)); for (int it = cw; it < CONV_PRO; it += 896) conv_ordered(it, F.lane); }
.LBB0_235:
	s_sleep 80
	s_add_i32 s10, s41, 0x380
	s_cmpk_gt_i32 s41, 0x4ddf
	s_mov_b32 s41, s10
	s_cbranch_scc1 .LBB0_299
